# P0 tail: rope-table loop with its 8 position loads issued up front, p->bf16 loop with its 8 loads batched; P4 (LoRA-up operand build): IEEE 1/x and 2/x expansions -> v_rcp_f32
# baseline (speedup 1.0000x reference)
; DI void prologue_rows(const float* const* in, unsigned char* ws, bf16* xb  , int gw, int NGW, int lane) {
;     ...
;     const int* pos = (const int*)in[I_POS]; float* rc = (float*)(ws + WS_RCOS); float* rsn = (float*)(ws + WS_RSIN);
;     for (int e = gw * 64 + lane; e < M * 64; e += NGW * 64) {
;         const int m = e >> 6, i = e & 63; double inv = 1.0; for (int j = 0; j < i; ++j) inv *= 0.8659643233600653523;
;         const double ang = (double)pos[m] * inv;
.Lrope_inv_done:
	s_or_b64 exec, exec, s[2:3]
	s_cmp_eq_u32 s6, 0x20000
	s_cbranch_scc0 .LBB0_203
	v_mov_b32_e32 v42, v22
	v_ashrrev_i32_e32 v26, 6, v42
	v_ashrrev_i32_e32 v27, 31, v26
	v_lshl_add_u64 v[26:27], v[26:27], 2, s[12:13]
	global_load_dword v34, v[26:27], off
	v_add_u32_e32 v42, s6, v42
	v_ashrrev_i32_e32 v26, 6, v42
	v_ashrrev_i32_e32 v27, 31, v26
	v_lshl_add_u64 v[26:27], v[26:27], 2, s[12:13]
	global_load_dword v35, v[26:27], off
	v_add_u32_e32 v42, s6, v42
	v_ashrrev_i32_e32 v26, 6, v42
	v_ashrrev_i32_e32 v27, 31, v26
	v_lshl_add_u64 v[26:27], v[26:27], 2, s[12:13]
	global_load_dword v36, v[26:27], off
	v_add_u32_e32 v42, s6, v42
	v_ashrrev_i32_e32 v26, 6, v42
	v_ashrrev_i32_e32 v27, 31, v26
	v_lshl_add_u64 v[26:27], v[26:27], 2, s[12:13]
	global_load_dword v37, v[26:27], off
	v_add_u32_e32 v42, s6, v42
	v_ashrrev_i32_e32 v26, 6, v42
	v_ashrrev_i32_e32 v27, 31, v26
	v_lshl_add_u64 v[26:27], v[26:27], 2, s[12:13]
	global_load_dword v38, v[26:27], off
	v_add_u32_e32 v42, s6, v42
	v_ashrrev_i32_e32 v26, 6, v42
	v_ashrrev_i32_e32 v27, 31, v26
	v_lshl_add_u64 v[26:27], v[26:27], 2, s[12:13]
	global_load_dword v39, v[26:27], off
	v_add_u32_e32 v42, s6, v42
	v_ashrrev_i32_e32 v26, 6, v42
	v_ashrrev_i32_e32 v27, 31, v26
	v_lshl_add_u64 v[26:27], v[26:27], 2, s[12:13]
	global_load_dword v40, v[26:27], off
	v_add_u32_e32 v42, s6, v42
	v_ashrrev_i32_e32 v26, 6, v42
	v_ashrrev_i32_e32 v27, 31, v26
	v_lshl_add_u64 v[26:27], v[26:27], 2, s[12:13]
	global_load_dword v41, v[26:27], off
	v_add_u32_e32 v42, s6, v42
	s_waitcnt vmcnt(0)
	s_branch .Lr2_203

; DI void prologue_rows(const float* const* in, unsigned char* ws, bf16* xb  , int gw, int NGW, int lane) {
;     ...
;         const int m = e >> 6, i = e & 63; double inv = 1.0; for (int j = 0; j < i; ++j) inv *= 0.8659643233600653523;
;         const double ang = (double)pos[m] * inv;
;         const double qd = __builtin_rint(ang * 0.63661977236758134308); const int qi = (int)((long long)qd & 3);
;         double r = __builtin_fma(-qd, 1.5707963267948965580, ang); r = __builtin_fma(-qd, 6.1232339957367658860e-17, r);
;         const double r2 = r * r;
;         const double sn = r * (1.0 + r2 * (-1.0 / 6 + r2 * (1.0 / 120 + r2 * (-1.0 / 5040 + r2 * (1.0 / 362880 + r2 * (-1.0 / 39916800 + r2 * (1.0 / 6227020800.0)))))));
;         const double cs = 1.0 + r2 * (-0.5 + r2 * (1.0 / 24 + r2 * (-1.0 / 720 + r2 * (1.0 / 40320 + r2 * (-1.0 / 3628800 + r2 * (1.0 / 479001600.0 + r2 * (-1.0 / 87178291200.0)))))));
;         const double c4 = (qi == 0) ? cs : (qi == 1) ? -sn : (qi == 2) ? -cs : sn;
;         const double s4 = (qi == 0) ? sn : (qi == 1) ? cs : (qi == 2) ? -sn : -cs;
;         rc[e] = (float)c4; rsn[e] = (float)s4;
.Lr2_203:
	v_mov_b64_e32 v[24:25], v[32:33]
	v_mov_b32_e32 v23, v34
	v_mov_b32_e32 v34, v35
	v_mov_b32_e32 v35, v36
	v_mov_b32_e32 v36, v37
	v_mov_b32_e32 v37, v38
	v_mov_b32_e32 v38, v39
	v_mov_b32_e32 v39, v40
	v_mov_b32_e32 v40, v41
	v_cvt_f64_i32_e32 v[26:27], v23
	v_mul_f64 v[24:25], v[24:25], v[26:27]
	v_mul_f64 v[26:27], v[24:25], s[22:23]
	v_rndne_f64_e32 v[26:27], v[26:27]
	v_ldexp_f64 v[28:29], v[26:27], s7
	v_fmac_f64_e32 v[24:25], s[24:25], v[26:27]
	v_mov_b64_e32 v[30:31], v[26:27]
	v_floor_f64_e32 v[28:29], v[28:29]
	v_fmac_f64_e32 v[24:25], s[26:27], v[26:27]
	v_fmac_f64_e32 v[30:31], 0xc1f00000, v[28:29]
	v_mul_f64 v[26:27], v[24:25], v[24:25]
	v_cvt_u32_f64_e32 v23, v[30:31]
	v_fma_f64 v[30:31], s[30:31], v[26:27], v[12:13]
	v_fma_f64 v[28:29], s[28:29], v[26:27], v[2:3]
	v_fma_f64 v[30:31], v[26:27], v[30:31], v[14:15]
	v_fma_f64 v[28:29], v[26:27], v[28:29], v[4:5]
	v_fma_f64 v[30:31], v[26:27], v[30:31], v[16:17]
	v_fma_f64 v[28:29], v[26:27], v[28:29], v[6:7]
	v_fma_f64 v[30:31], v[26:27], v[30:31], v[18:19]
	v_fma_f64 v[28:29], v[26:27], v[28:29], v[8:9]
	v_fma_f64 v[30:31], v[26:27], v[30:31], v[20:21]
	v_fma_f64 v[28:29], v[26:27], v[28:29], v[10:11]
	v_fma_f64 v[30:31], v[26:27], v[30:31], -0.5
	v_and_b32_e32 v23, 3, v23
	v_fma_f64 v[28:29], v[26:27], v[28:29], 1.0
	v_fma_f64 v[26:27], v[26:27], v[30:31], 1.0
	v_cmp_eq_u32_e64 s[0:1], 0, v23
	v_mul_f64 v[24:25], v[24:25], v[28:29]
	v_cmp_ne_u32_e64 s[2:3], 0, v23
	v_mov_b64_e32 v[28:29], v[26:27]
	s_and_saveexec_b64 s[34:35], s[2:3]
	s_cbranch_execz .Lr2_202
	v_cmp_ne_u32_e64 s[2:3], 1, v23
	v_xor_b32_e32 v29, 0x80000000, v25
	v_mov_b32_e32 v28, v24
	s_and_saveexec_b64 s[36:37], s[2:3]
	s_xor_b64 s[36:37], exec, s[36:37]
	s_cbranch_execz .Lr2_201
	v_xor_b32_e32 v28, 0x80000000, v27
	v_cmp_eq_u32_e64 s[2:3], 2, v23
	s_nop 1
	v_cndmask_b32_e64 v29, v25, v28, s[2:3]
	v_cndmask_b32_e64 v28, v24, v26, s[2:3]
	s_branch .Lr2_201

; #define GAS __attribute__((address_space(1)))
; DI unsigned pk2(float lo, float hi) { return f2bf(lo) | (f2bf(hi) << 16); }
; DI void prologue_rows(const float* const* in, unsigned char* ws, bf16* xb  , int gw, int NGW, int lane) {
;     ...
;     const float* p = in[I_P]; bf16* pb = (bf16*)(ws + WS_PB);
;     for (int e = gw * 64 + lane; e < M * DPLE / 4; e += NGW * 64) { const f32x4 v = ((const GAS f32x4*)p)[e]; v2u w; w.x = pk2(v.x, v.y); w.y = pk2(v.z, v.w); ((GAS v2u*)pb)[e] = w; }
.LBB0_210:
	s_or_b64 exec, exec, s[18:19]
	v_readlane_b32 s0, v254, 7
	v_readlane_b32 s1, v254, 8
	s_load_dwordx2 s[0:1], s[0:1], 0x108
	v_ashrrev_i32_e32 v1, 31, v0
	v_mov_b32_e32 v4, s10
	v_mov_b32_e32 v5, s11
	s_ashr_i32 s7, s6, 31
	s_waitcnt lgkmcnt(0)
	v_lshl_add_u64 v[2:3], v[0:1], 3, s[0:1]
	s_mov_b64 s[0:1], 0xd00000
	v_lshl_add_u64 v[2:3], v[2:3], 0, s[0:1]
	s_lshl_b64 s[0:1], s[6:7], 3
	v_lshl_add_u64 v[4:5], v[0:1], 4, v[4:5]
	s_lshl_b64 s[2:3], s[6:7], 4
	s_mov_b64 s[8:9], 0
	s_movk_i32 s7, 0x7fff
	s_mov_b32 s10, 0xffff0000
	s_mov_b32 s11, 0xfffff
	s_cmp_eq_u32 s6, 0x20000
	s_cbranch_scc0 .LBB0_211
	global_load_dwordx4 v[6:9], v[4:5], off
	v_lshl_add_u64 v[4:5], v[4:5], 0, s[2:3]
	global_load_dwordx4 v[10:13], v[4:5], off
	v_lshl_add_u64 v[4:5], v[4:5], 0, s[2:3]
	global_load_dwordx4 v[14:17], v[4:5], off
	v_lshl_add_u64 v[4:5], v[4:5], 0, s[2:3]
	global_load_dwordx4 v[18:21], v[4:5], off
	v_lshl_add_u64 v[4:5], v[4:5], 0, s[2:3]
	global_load_dwordx4 v[22:25], v[4:5], off
	v_lshl_add_u64 v[4:5], v[4:5], 0, s[2:3]
	global_load_dwordx4 v[26:29], v[4:5], off
	v_lshl_add_u64 v[4:5], v[4:5], 0, s[2:3]
	global_load_dwordx4 v[30:33], v[4:5], off
	v_lshl_add_u64 v[4:5], v[4:5], 0, s[2:3]
	global_load_dwordx4 v[34:37], v[4:5], off
	v_lshl_add_u64 v[4:5], v[4:5], 0, s[2:3]
	s_waitcnt vmcnt(7)
	v_bfe_u32 v1, v6, 16, 1
	v_bfe_u32 v42, v7, 16, 1
	v_bfe_u32 v43, v8, 16, 1
	v_bfe_u32 v44, v9, 16, 1
	v_add3_u32 v1, v6, v1, s7
	v_add3_u32 v38, v7, v42, s7
	v_add3_u32 v43, v8, v43, s7
	v_add3_u32 v39, v9, v44, s7
	v_lshrrev_b32_e32 v1, 16, v1
	v_lshrrev_b32_e32 v43, 16, v43
	v_and_or_b32 v38, v38, s10, v1
	v_and_or_b32 v39, v39, s10, v43
	global_store_dwordx2 v[2:3], v[38:39], off
	v_lshl_add_u64 v[2:3], v[2:3], 0, s[0:1]
	s_waitcnt vmcnt(7)
	v_bfe_u32 v1, v10, 16, 1
	v_bfe_u32 v42, v11, 16, 1
	v_bfe_u32 v43, v12, 16, 1
	v_bfe_u32 v44, v13, 16, 1
	v_add3_u32 v1, v10, v1, s7
	v_add3_u32 v40, v11, v42, s7
	v_add3_u32 v43, v12, v43, s7
	v_add3_u32 v41, v13, v44, s7
	v_lshrrev_b32_e32 v1, 16, v1
	v_lshrrev_b32_e32 v43, 16, v43
	v_and_or_b32 v40, v40, s10, v1
	v_and_or_b32 v41, v41, s10, v43
	global_store_dwordx2 v[2:3], v[40:41], off
	v_lshl_add_u64 v[2:3], v[2:3], 0, s[0:1]
	s_waitcnt vmcnt(7)
	v_bfe_u32 v1, v14, 16, 1
	v_bfe_u32 v42, v15, 16, 1
	v_bfe_u32 v43, v16, 16, 1
	v_bfe_u32 v44, v17, 16, 1
	v_add3_u32 v1, v14, v1, s7
	v_add3_u32 v38, v15, v42, s7
	v_add3_u32 v43, v16, v43, s7
	v_add3_u32 v39, v17, v44, s7
	v_lshrrev_b32_e32 v1, 16, v1
	v_lshrrev_b32_e32 v43, 16, v43
	v_and_or_b32 v38, v38, s10, v1
	v_and_or_b32 v39, v39, s10, v43
	global_store_dwordx2 v[2:3], v[38:39], off
	v_lshl_add_u64 v[2:3], v[2:3], 0, s[0:1]
	s_waitcnt vmcnt(7)
	v_bfe_u32 v1, v18, 16, 1
	v_bfe_u32 v42, v19, 16, 1
	v_bfe_u32 v43, v20, 16, 1
	v_bfe_u32 v44, v21, 16, 1
	v_add3_u32 v1, v18, v1, s7
	v_add3_u32 v40, v19, v42, s7
	v_add3_u32 v43, v20, v43, s7
	v_add3_u32 v41, v21, v44, s7
	v_lshrrev_b32_e32 v1, 16, v1
	v_lshrrev_b32_e32 v43, 16, v43
	v_and_or_b32 v40, v40, s10, v1
	v_and_or_b32 v41, v41, s10, v43
	global_store_dwordx2 v[2:3], v[40:41], off
	v_lshl_add_u64 v[2:3], v[2:3], 0, s[0:1]
	s_waitcnt vmcnt(7)
	v_bfe_u32 v1, v22, 16, 1
	v_bfe_u32 v42, v23, 16, 1
	v_bfe_u32 v43, v24, 16, 1
	v_bfe_u32 v44, v25, 16, 1
	v_add3_u32 v1, v22, v1, s7
	v_add3_u32 v38, v23, v42, s7
	v_add3_u32 v43, v24, v43, s7
	v_add3_u32 v39, v25, v44, s7
	v_lshrrev_b32_e32 v1, 16, v1
	v_lshrrev_b32_e32 v43, 16, v43
	v_and_or_b32 v38, v38, s10, v1
	v_and_or_b32 v39, v39, s10, v43
	global_store_dwordx2 v[2:3], v[38:39], off
	v_lshl_add_u64 v[2:3], v[2:3], 0, s[0:1]
	s_waitcnt vmcnt(7)
	v_bfe_u32 v1, v26, 16, 1
	v_bfe_u32 v42, v27, 16, 1
	v_bfe_u32 v43, v28, 16, 1
	v_bfe_u32 v44, v29, 16, 1
	v_add3_u32 v1, v26, v1, s7
	v_add3_u32 v40, v27, v42, s7
	v_add3_u32 v43, v28, v43, s7
	v_add3_u32 v41, v29, v44, s7
	v_lshrrev_b32_e32 v1, 16, v1
	v_lshrrev_b32_e32 v43, 16, v43
	v_and_or_b32 v40, v40, s10, v1
	v_and_or_b32 v41, v41, s10, v43
	global_store_dwordx2 v[2:3], v[40:41], off
	v_lshl_add_u64 v[2:3], v[2:3], 0, s[0:1]
	s_waitcnt vmcnt(7)
	v_bfe_u32 v1, v30, 16, 1
	v_bfe_u32 v42, v31, 16, 1
	v_bfe_u32 v43, v32, 16, 1
	v_bfe_u32 v44, v33, 16, 1
	v_add3_u32 v1, v30, v1, s7
	v_add3_u32 v38, v31, v42, s7
	v_add3_u32 v43, v32, v43, s7
	v_add3_u32 v39, v33, v44, s7
	v_lshrrev_b32_e32 v1, 16, v1
	v_lshrrev_b32_e32 v43, 16, v43
	v_and_or_b32 v38, v38, s10, v1
	v_and_or_b32 v39, v39, s10, v43
	global_store_dwordx2 v[2:3], v[38:39], off
	v_lshl_add_u64 v[2:3], v[2:3], 0, s[0:1]
	s_waitcnt vmcnt(7)
	v_bfe_u32 v1, v34, 16, 1
	v_bfe_u32 v42, v35, 16, 1
	v_bfe_u32 v43, v36, 16, 1
	v_bfe_u32 v44, v37, 16, 1
	v_add3_u32 v1, v34, v1, s7
	v_add3_u32 v40, v35, v42, s7
	v_add3_u32 v43, v36, v43, s7
	v_add3_u32 v41, v37, v44, s7
	v_lshrrev_b32_e32 v1, 16, v1
	v_lshrrev_b32_e32 v43, 16, v43
	v_and_or_b32 v40, v40, s10, v1
	v_and_or_b32 v41, v41, s10, v43
	global_store_dwordx2 v[2:3], v[40:41], off
	v_lshl_add_u64 v[2:3], v[2:3], 0, s[0:1]
	v_lshl_add_u32 v0, s6, 3, v0
	v_cmp_lt_i32_e32 vcc, s11, v0
	s_mov_b64 s[8:9], exec
	s_branch .LBB0_212

; DI float sigmoidf_(float z) { return 1.0f / (1.0f + __expf(-z)); }
; DI void build_alora(unsigned char* ws, int gtid, int NT) {
;     ...
;             if (which == 0) {
; #pragma unroll
;                 for (int t = 0; t < 4; ++t) { o0[t] = 1.0f - 2.0f / (__expf(2.0f * o0[t]) + 1.0f); o1[t] = 1.0f - 2.0f / (__expf(2.0f * o1[t]) + 1.0f); } }
;             if (which == 2) {
; #pragma unroll
;                 for (int t = 0; t < 4; ++t) { o0[t] = sigmoidf_(o0[t]); o1[t] = sigmoidf_(o1[t]); } }
.LBB0_500:
	s_or_b64 exec, exec, s[18:19]
	s_waitcnt vmcnt(0)
	v_lshlrev_b32_e32 v16, 16, v0
	v_and_b32_e32 v17, 0xffff0000, v0
	v_lshlrev_b32_e32 v0, 16, v1
	v_and_b32_e32 v1, 0xffff0000, v1
	v_lshlrev_b32_e32 v18, 16, v2
	v_and_b32_e32 v19, 0xffff0000, v2
	v_lshlrev_b32_e32 v28, 16, v3
	v_and_b32_e32 v29, 0xffff0000, v3
	v_pk_add_f32 v[2:3], v[14:15], v[0:1]
	v_pk_add_f32 v[0:1], v[12:13], v[16:17]
	v_pk_add_f32 v[6:7], v[6:7], v[28:29]
	v_pk_add_f32 v[4:5], v[4:5], v[18:19]
	s_and_saveexec_b64 s[2:3], vcc
	s_cbranch_execz .LBB0_502
	v_add_f32_e32 v0, v0, v0
	v_add_f32_e32 v1, v1, v1
	v_mul_f32_e32 v0, 0x3fb8aa3b, v0
	v_mul_f32_e32 v1, 0x3fb8aa3b, v1
	v_exp_f32_e32 v0, v0
	v_exp_f32_e32 v1, v1
	v_add_f32_e32 v2, v2, v2
	v_add_f32_e32 v3, v3, v3
	v_mul_f32_e32 v2, 0x3fb8aa3b, v2
	v_pk_add_f32 v[0:1], v[0:1], 1.0 op_sel_hi:[1,0]
	v_mul_f32_e32 v3, 0x3fb8aa3b, v3
	v_exp_f32_e32 v2, v2
	v_exp_f32_e32 v3, v3
	v_add_f32_e32 v4, v4, v4
	v_rcp_f32_e32 v0, v0
	s_nop 0
	v_add_f32_e32 v0, v0, v0
	v_pk_add_f32 v[2:3], v[2:3], 1.0 op_sel_hi:[1,0]
	v_rcp_f32_e32 v1, v1
	s_nop 0
	v_add_f32_e32 v1, v1, v1
	v_add_f32_e32 v5, v5, v5
	v_rcp_f32_e32 v2, v2
	s_nop 0
	v_add_f32_e32 v2, v2, v2
	v_mul_f32_e32 v4, 0x3fb8aa3b, v4
	v_mul_f32_e32 v5, 0x3fb8aa3b, v5
	v_exp_f32_e32 v4, v4
	v_exp_f32_e32 v5, v5
	s_nop 0
	v_pk_add_f32 v[4:5], v[4:5], 1.0 op_sel_hi:[1,0]
	v_rcp_f32_e32 v3, v3
	s_nop 0
	v_add_f32_e32 v3, v3, v3
	v_add_f32_e32 v6, v6, v6
	v_add_f32_e32 v7, v7, v7
	v_mul_f32_e32 v6, 0x3fb8aa3b, v6
	v_mul_f32_e32 v7, 0x3fb8aa3b, v7
	v_exp_f32_e32 v6, v6
	v_exp_f32_e32 v7, v7
	v_rcp_f32_e32 v4, v4
	s_nop 0
	v_add_f32_e32 v4, v4, v4
	v_pk_add_f32 v[6:7], v[6:7], 1.0 op_sel_hi:[1,0]
	v_rcp_f32_e32 v5, v5
	s_nop 0
	v_add_f32_e32 v5, v5, v5
	v_sub_f32_e32 v3, 1.0, v3
	v_rcp_f32_e32 v6, v6
	s_nop 0
	v_add_f32_e32 v6, v6, v6
	v_sub_f32_e32 v2, 1.0, v2
	v_rcp_f32_e32 v7, v7
	s_nop 0
	v_add_f32_e32 v7, v7, v7
	v_sub_f32_e32 v1, 1.0, v1
	v_sub_f32_e32 v0, 1.0, v0
	v_sub_f32_e32 v7, 1.0, v7
	v_sub_f32_e32 v6, 1.0, v6
	v_sub_f32_e32 v5, 1.0, v5
	v_sub_f32_e32 v4, 1.0, v4
.LBB0_502:
	s_or_b64 exec, exec, s[2:3]
	s_and_saveexec_b64 s[2:3], s[0:1]
	s_cbranch_execz .LBB0_493
	v_mul_f32_e32 v2, 0xbfb8aa3b, v2
	v_mul_f32_e32 v3, 0xbfb8aa3b, v3
	v_exp_f32_e32 v2, v2
	v_exp_f32_e32 v3, v3
	v_mul_f32_e32 v0, 0xbfb8aa3b, v0
	v_mul_f32_e32 v1, 0xbfb8aa3b, v1
	v_exp_f32_e32 v0, v0
	v_pk_add_f32 v[2:3], v[2:3], 1.0 op_sel_hi:[1,0]
	v_exp_f32_e32 v1, v1
	s_nop 0
	v_pk_add_f32 v[0:1], v[0:1], 1.0 op_sel_hi:[1,0]
	v_mul_f32_e32 v6, 0xbfb8aa3b, v6
	v_mul_f32_e32 v7, 0xbfb8aa3b, v7
	v_rcp_f32_e32 v3, v3
	v_exp_f32_e32 v6, v6
	v_rcp_f32_e32 v2, v2
	v_exp_f32_e32 v7, v7
	v_rcp_f32_e32 v1, v1
	v_pk_add_f32 v[6:7], v[6:7], 1.0 op_sel_hi:[1,0]
	v_rcp_f32_e32 v0, v0
	v_mul_f32_e32 v4, 0xbfb8aa3b, v4
	v_mul_f32_e32 v5, 0xbfb8aa3b, v5
	v_exp_f32_e32 v4, v4
	v_exp_f32_e32 v5, v5
	v_rcp_f32_e32 v7, v7
	v_pk_add_f32 v[4:5], v[4:5], 1.0 op_sel_hi:[1,0]
	v_rcp_f32_e32 v6, v6
	v_rcp_f32_e32 v5, v5
	v_rcp_f32_e32 v4, v4
	s_branch .LBB0_493
